# v29 + layer-1 PLE-proj weight conversion moved from the prologue to the layer-0 w_in GEMM tail slot
# speedup vs baseline: 1.0116x; 1.0021x over previous
; #define LAS __attribute__((address_space(3)))
; __device__ __forceinline__ void convert_range(unsigned char* lds, int lo, int hi, int w, int nworkers, int wave, int lane) {
;     const XItem* tab = (const XItem*)(lds + 8 * 16640);
;     LAS float* scr = (LAS float*)((LAS unsigned char*)lds + wave * 16640);
;     int it = lo + w; if (it >= hi) return;
;     f32x4 v[16]; float gv[16]; ItemPos p = item_load(tab, it, lane, v, gv);
; __global__ void __launch_bounds__(NTHREADS, 2) mega_fwd(KArgs a_unused) {
;     ...
;         if (((32 * 44) % G != 0) && ((32 * 18) % G != 0)) { convert_range(lds, 0, 5632, gw, NGW, wave, lane); convert_range(lds, 10752, 17408, gw, NGW, wave, lane); convert_range(lds, 21248, ITEMS_L, gw, NGW, wave, lane); convert_range(lds, ITEMS_L + 21248, 2 * ITEMS_L, gw, NGW, wave, lane); }
.LBB0_226:
	s_andn2_b64 vcc, exec, s[18:19]
	s_mov_b32 s0, 1
	s_branch .LBB0_295
	s_add_i32 s20, s12, 0xa680
	s_mov_b32 s1, s20
	s_mov_b32 s2, 2
	s_mov_b32 s3, 0
	v_bfrev_b32_e32 v2, 1
	v_bfrev_b32_e32 v3, 1

; #define LAS __attribute__((address_space(3)))
; #define GW_DECL const int wv_ = launder_s(g_wave), lane = opaque_lane(), tid = (wv_ << 6) | lane, gw = BXL() * NWAVES + wv_; (void)tid; (void)lane; (void)gw
; #define BXL() ({ int _b = bx; asm volatile("" : "+s"(_b)); _b; })
; __device__ __forceinline__ void convert_range(unsigned char* lds, int lo, int hi, int w, int nworkers, int wave, int lane) {
;     const XItem* tab = (const XItem*)(lds + 8 * 16640);
;     LAS float* scr = (LAS float*)((LAS unsigned char*)lds + wave * 16640);
;     int it = lo + w; if (it >= hi) return;
;     f32x4 v[16]; float gv[16]; ItemPos p = item_load(tab, it, lane, v, gv);
; __global__ void __launch_bounds__(NTHREADS, 2) mega_fwd(KArgs a_unused) {
;     ...
;           if (((32 * 44) % G != 0) && ((32 * 18) % G != 0)) { const int rem_ = (32 * 18) % G; const int bxt_ = BXL(); if (rem_ != 0 && bxt_ >= rem_) { GW_DECL; convert_range(lds, (l == 0 ? 17408 : ITEMS_L + 10752), (l == 0 ? 21248 : ITEMS_L + 17408), (bxt_ - rem_) * NWAVES + wv_, (G - rem_) * NWAVES, wv_, lane); convert_range(lds, (l == 0 ? ITEMS_L : 0), (l == 0 ? ITEMS_L + 2816 : 0), (bxt_ - rem_) * NWAVES + wv_, (G - rem_) * NWAVES, wv_, lane); __syncthreads(); } } }
.LBB0_814:
	v_readlane_b32 s2, v255, 29
	v_readlane_b32 s3, v255, 30
	s_and_b64 s[2:3], s[2:3], exec
	s_cselect_b32 s1, 0xa680, 0
	s_cselect_b32 s16, 0xa700, 0
	s_add_i32 s15, s15, s1
	s_cmp_ge_i32 s15, s16
	s_cbranch_scc1 .LBB0_883
	s_mov_b32 s1, s15
	s_mov_b32 s2, 2
	s_mov_b32 s3, 1
	s_mov_b32 s4, 0
	v_bfrev_b32_e32 v0, 1
	v_bfrev_b32_e32 v2, 1
